# r55 layout variant: compression-MLP unit code shifted by 4 bytes, later code by 8 (code alignment tuning)
# baseline (speedup 1.0000x reference)
.LBB0_238:
	s_or_b64 exec, exec, s[2:3]
	v_readlane_b32 s12, v251, 32
	s_lshl_b64 s[2:3], s[88:89], 9
	v_readlane_b32 s16, v251, 36
	v_readlane_b32 s17, v251, 37
	s_add_u32 s2, s16, s2
	s_addc_u32 s3, s17, s3
	v_lshl_add_u64 v[18:19], v[106:107], 2, s[2:3]
	s_lshr_b32 s2, s91, 1
	s_and_b32 s12, s2, 14
	s_lshl_b32 s2, s91, 6
	v_readlane_b32 s13, v251, 33
	s_addk_i32 s2, 0x5000
	v_readlane_b32 s14, v251, 34
	s_and_b32 s13, s2, 0x7800
	s_lshl_b32 s2, s12, 7
	v_readlane_b32 s15, v251, 35
	s_or_b32 s14, s2, s13
	global_load_dword v108, v[18:19], off
	v_add_u32_e32 v18, s14, v106
	v_mov_b64_e32 v[112:113], s[58:59]
	s_movk_i32 s15, 0x1e00
	v_lshrrev_b32_e32 v21, 1, v20
	v_mad_i64_i32 v[18:19], s[2:3], v18, s15, v[112:113]
	s_lshl_b32 s88, s10, 7
	v_and_b32_e32 v110, 32, v21
	v_lshl_add_u64 v[18:19], v[18:19], 0, s[88:89]
	v_lshlrev_b32_e32 v130, 1, v110
	v_mov_b32_e32 v131, v0
	v_lshl_add_u64 v[18:19], v[18:19], 0, v[130:131]
	v_lshlrev_b32_e32 v132, 1, v1
	v_mov_b32_e32 v133, v0
	v_lshl_add_u64 v[18:19], v[18:19], 0, v[132:133]
	v_ashrrev_i32_e32 v111, 2, v20
	global_load_dwordx2 v[128:129], v[18:19], off offset:2048
	global_load_dwordx2 v[124:125], v[18:19], off offset:2064
	global_load_dwordx2 v[120:121], v[18:19], off offset:2080
	global_load_dwordx2 v[116:117], v[18:19], off offset:2096
	global_load_dwordx2 v[126:127], v[18:19], off offset:3072
	global_load_dwordx2 v[122:123], v[18:19], off offset:3088
	global_load_dwordx2 v[118:119], v[18:19], off offset:3104
	global_load_dwordx2 v[114:115], v[18:19], off offset:3120
	v_add_u32_e32 v18, s14, v111
	v_mad_i64_i32 v[18:19], s[2:3], v18, s15, v[112:113]
	v_lshlrev_b32_e32 v20, 4, v20
	s_lshl_b32 s10, s10, 8
	v_readlane_b32 s2, v253, 63
	v_and_b32_e32 v26, 48, v20
	s_add_u32 s2, s2, s10
	v_readlane_b32 s3, v254, 0
	v_lshl_add_u64 v[18:19], v[18:19], 0, s[88:89]
	v_lshlrev_b32_e32 v136, 1, v26
	v_mov_b32_e32 v137, v0
	s_addc_u32 s3, s3, 0
	v_readlane_b32 s11, v254, 1
	v_lshl_add_u64 v[22:23], v[18:19], 0, v[136:137]
	s_add_u32 s10, s11, s10
	v_readlane_b32 s11, v254, 4
	v_lshlrev_b32_e32 v134, 2, v26
	global_load_dwordx4 v[18:21], v[22:23], off offset:2576
	s_nop 0
	global_load_dwordx4 v[22:25], v[22:23], off offset:2560
	s_addc_u32 s11, s11, 0
	global_load_dwordx4 v[26:29], v134, s[2:3] offset:48
	global_load_dwordx4 v[30:33], v134, s[2:3] offset:32
	global_load_dwordx4 v[34:37], v134, s[2:3] offset:16
	global_load_dwordx4 v[38:41], v134, s[2:3]
	global_load_dwordx4 v[42:45], v134, s[10:11] offset:48
	global_load_dwordx4 v[46:49], v134, s[10:11] offset:32
	global_load_dwordx4 v[50:53], v134, s[10:11] offset:16
	global_load_dwordx4 v[54:57], v134, s[10:11]
	v_lshlrev_b32_e32 v110, 2, v110
	v_lshlrev_b32_e32 v109, 2, v109
	v_add3_u32 v186, 0, v110, v109
	v_mov_b32_e32 v110, 0x880
	v_mad_u32_u24 v192, v1, s79, v110
	v_mov_b32_e32 v110, 0x1100
	v_mad_u32_u24 v193, v1, s79, v110
	v_mov_b32_e32 v110, 0x1980
	v_mad_u32_u24 v195, v1, s79, v110
	v_mov_b32_e32 v110, 0x2200
	v_mad_u32_u24 v204, v1, s79, v110
	v_mov_b32_e32 v110, 0x2a80
	v_mul_lo_u32 v135, v111, s79
	s_bitset1_b32 s14, 7
	v_mad_u32_u24 v205, v1, s79, v110
	v_mov_b32_e32 v110, 0x3300
	v_add3_u32 v134, 0, v135, v134
	v_add_u32_e32 v109, s14, v106
	v_add_u32_e32 v135, s14, v111
	v_mad_u32_u24 v206, v1, s79, v110
	v_mov_b32_e32 v110, 0x3b80
	v_mad_u32_u24 v207, v1, s79, v110
	v_mad_i64_i32 v[110:111], s[2:3], v109, s15, v[112:113]
	v_mad_i64_i32 v[112:113], s[2:3], v135, s15, v[112:113]
	v_cmp_le_i32_e32 vcc, v1, v106
	v_or_b32_e32 v138, 2, v1
	v_lshl_add_u64 v[112:113], v[112:113], 0, s[88:89]
	s_waitcnt vmcnt(19)
	v_cndmask_b32_e32 v135, 0, v6, vcc
	v_cmp_lt_i32_e32 vcc, v1, v106
	v_or_b32_e32 v139, 3, v1
	v_lshl_add_u64 v[112:113], v[112:113], 0, v[136:137]
	v_cndmask_b32_e32 v136, 0, v7, vcc
	v_cmp_le_i32_e32 vcc, v138, v106
	v_or_b32_e32 v140, 8, v1
	v_or_b32_e32 v141, 9, v1
	v_cndmask_b32_e32 v137, 0, v8, vcc
	v_cmp_le_i32_e32 vcc, v139, v106
	v_or_b32_e32 v142, 10, v1
	v_or_b32_e32 v143, 11, v1
	v_cndmask_b32_e32 v138, 0, v9, vcc
	v_cmp_le_i32_e32 vcc, v140, v106
	v_or_b32_e32 v144, 16, v1
	v_or_b32_e32 v145, 17, v1
	v_cndmask_b32_e32 v139, 0, v2, vcc
	v_cmp_le_i32_e32 vcc, v141, v106
	v_or_b32_e32 v146, 18, v1
	v_or_b32_e32 v147, 19, v1
	v_cndmask_b32_e32 v140, 0, v3, vcc
	v_cmp_le_i32_e32 vcc, v142, v106
	v_or_b32_e32 v148, 24, v1
	v_or_b32_e32 v149, 25, v1
	v_cndmask_b32_e32 v141, 0, v4, vcc
	v_cmp_le_i32_e32 vcc, v143, v106
	v_or_b32_e32 v150, 26, v1
	v_or_b32_e32 v151, 27, v1
	v_cndmask_b32_e32 v142, 0, v5, vcc
	v_cmp_le_i32_e32 vcc, v144, v106
	v_or_b32_e32 v152, 32, v1
	v_or_b32_e32 v153, 33, v1
	v_cndmask_b32_e32 v143, 0, v14, vcc
	v_cmp_le_i32_e32 vcc, v145, v106
	v_or_b32_e32 v154, 34, v1
	v_or_b32_e32 v155, 35, v1
	v_cndmask_b32_e32 v144, 0, v15, vcc
	v_cmp_le_i32_e32 vcc, v146, v106
	v_or_b32_e32 v156, 40, v1
	v_or_b32_e32 v157, 41, v1
	v_cndmask_b32_e32 v145, 0, v16, vcc
	v_cmp_le_i32_e32 vcc, v147, v106
	v_or_b32_e32 v158, 42, v1
	v_or_b32_e32 v159, 43, v1
	v_cndmask_b32_e32 v146, 0, v17, vcc
	v_cmp_le_i32_e32 vcc, v148, v106
	v_or_b32_e32 v160, 48, v1
	v_or_b32_e32 v161, 49, v1
	v_cndmask_b32_e32 v147, 0, v10, vcc
	v_cmp_le_i32_e32 vcc, v149, v106
	v_or_b32_e32 v166, 50, v1
	v_or_b32_e32 v167, 51, v1
	v_cndmask_b32_e32 v148, 0, v11, vcc
	v_cmp_le_i32_e32 vcc, v150, v106
	v_or_b32_e32 v168, 56, v1
	v_or_b32_e32 v169, 57, v1
	v_cndmask_b32_e32 v149, 0, v12, vcc
	v_cmp_le_i32_e32 vcc, v151, v106
	v_or_b32_e32 v170, 58, v1
	v_or_b32_e32 v171, 59, v1
	v_cndmask_b32_e32 v150, 0, v13, vcc
	v_cmp_le_i32_e32 vcc, v152, v106
	v_or_b32_e32 v172, 64, v1
	v_or_b32_e32 v173, 0x41, v1
	v_cndmask_b32_e32 v151, 0, v62, vcc
	v_cmp_le_i32_e32 vcc, v153, v106
	v_or_b32_e32 v174, 0x42, v1
	v_or_b32_e32 v175, 0x43, v1
	v_cndmask_b32_e32 v152, 0, v63, vcc
	v_cmp_le_i32_e32 vcc, v154, v106
	v_or_b32_e32 v176, 0x48, v1
	v_or_b32_e32 v177, 0x49, v1
	v_cndmask_b32_e32 v153, 0, v64, vcc
	v_cmp_le_i32_e32 vcc, v155, v106
	v_or_b32_e32 v178, 0x4a, v1
	v_or_b32_e32 v179, 0x4b, v1
	v_cndmask_b32_e32 v154, 0, v65, vcc
	v_cmp_le_i32_e32 vcc, v156, v106
	v_or_b32_e32 v180, 0x50, v1
	v_or_b32_e32 v181, 0x51, v1
	v_cndmask_b32_e32 v155, 0, v58, vcc
	v_cmp_le_i32_e32 vcc, v157, v106
	v_or_b32_e32 v197, 0x52, v1
	v_or_b32_e32 v198, 0x53, v1
	v_cndmask_b32_e32 v156, 0, v59, vcc
	v_cmp_le_i32_e32 vcc, v158, v106
	v_or_b32_e32 v199, 0x58, v1
	v_or_b32_e32 v200, 0x59, v1
	v_cndmask_b32_e32 v157, 0, v60, vcc
	v_cmp_le_i32_e32 vcc, v159, v106
	v_or_b32_e32 v201, 0x5a, v1
	v_or_b32_e32 v202, 0x5b, v1
	v_cndmask_b32_e32 v158, 0, v61, vcc
	v_cmp_le_i32_e32 vcc, v160, v106
	v_or_b32_e32 v203, 0x60, v1
	v_or_b32_e32 v208, 0x61, v1
	v_cndmask_b32_e32 v159, 0, v70, vcc
	v_cmp_le_i32_e32 vcc, v161, v106
	v_or_b32_e32 v209, 0x62, v1
	v_or_b32_e32 v210, 0x63, v1
	v_cndmask_b32_e32 v160, 0, v71, vcc
	v_cmp_le_i32_e32 vcc, v166, v106
	v_or_b32_e32 v211, 0x68, v1
	v_or_b32_e32 v212, 0x69, v1
	v_cndmask_b32_e32 v161, 0, v72, vcc
	v_cmp_le_i32_e32 vcc, v167, v106
	v_or_b32_e32 v213, 0x6a, v1
	v_or_b32_e32 v214, 0x6b, v1
	v_cndmask_b32_e32 v166, 0, v73, vcc
	v_cmp_le_i32_e32 vcc, v168, v106
	v_or_b32_e32 v215, 0x70, v1
	v_or_b32_e32 v216, 0x71, v1
	v_cndmask_b32_e32 v167, 0, v66, vcc
	v_cmp_le_i32_e32 vcc, v169, v106
	v_or_b32_e32 v217, 0x72, v1
	v_or_b32_e32 v218, 0x73, v1
	v_cndmask_b32_e32 v168, 0, v67, vcc
	v_cmp_le_i32_e32 vcc, v170, v106
	v_or_b32_e32 v219, 0x78, v1
	v_or_b32_e32 v220, 0x79, v1
	v_cndmask_b32_e32 v169, 0, v68, vcc
	v_cmp_le_i32_e32 vcc, v171, v106
	v_or_b32_e32 v221, 0x7a, v1
	s_add_u32 s2, s62, s88
	v_cndmask_b32_e32 v170, 0, v69, vcc
	v_cmp_le_i32_e32 vcc, v172, v106
	v_or_b32_e32 v222, 0x7b, v1
	v_lshl_add_u64 v[110:111], v[110:111], 0, s[88:89]
	v_cndmask_b32_e32 v171, 0, v78, vcc
	v_cmp_le_i32_e32 vcc, v173, v106
	s_addc_u32 s3, s63, 0
	v_readlane_b32 s18, v251, 38
	v_cndmask_b32_e32 v172, 0, v79, vcc
	v_cmp_le_i32_e32 vcc, v174, v106
	v_mul_u32_u24_e32 v187, 0x110, v1
	v_lshl_add_u64 v[110:111], v[110:111], 0, v[130:131]
	v_cndmask_b32_e32 v173, 0, v80, vcc
	v_cmp_le_i32_e32 vcc, v175, v106
	v_lshl_add_u64 v[2:3], s[2:3], 0, v[130:131]
	v_lshl_add_u64 v[110:111], v[110:111], 0, v[132:133]
	v_cndmask_b32_e32 v174, 0, v81, vcc
	v_cmp_le_i32_e32 vcc, v176, v106
	s_waitcnt vmcnt(18)
	v_mov_b32_e32 v109, v108
	v_lshl_add_u64 v[58:59], v[2:3], 0, v[132:133]
	v_cndmask_b32_e32 v175, 0, v74, vcc
	v_cmp_le_i32_e32 vcc, v177, v106
	s_mov_b32 s14, 0
	s_mov_b64 s[10:11], -1
	v_cndmask_b32_e32 v176, 0, v75, vcc
	v_cmp_le_i32_e32 vcc, v178, v106
	v_add_u32_e32 v130, v186, v187
	v_add_u32_e32 v131, v186, v192
	v_cndmask_b32_e32 v177, 0, v76, vcc
	v_cmp_le_i32_e32 vcc, v179, v106
	v_add_u32_e32 v132, v186, v193
	v_add_u32_e32 v133, v186, v195
	v_cndmask_b32_e32 v178, 0, v77, vcc
	v_cmp_le_i32_e32 vcc, v180, v106
	v_add_u32_e32 v204, v186, v204
	v_add_u32_e32 v205, v186, v205
	v_cndmask_b32_e32 v179, 0, v86, vcc
	v_cmp_le_i32_e32 vcc, v181, v106
	v_add_u32_e32 v206, v186, v206
	v_add_u32_e32 v207, v186, v207
	v_cndmask_b32_e32 v180, 0, v87, vcc
	v_cmp_le_i32_e32 vcc, v197, v106
	s_waitcnt vmcnt(13)
	v_mov_b64_e32 v[62:63], v[126:127]
	s_waitcnt vmcnt(12)
	v_mov_b64_e32 v[66:67], v[122:123]
	v_cndmask_b32_e32 v181, 0, v88, vcc
	v_cmp_le_i32_e32 vcc, v198, v106
	s_waitcnt vmcnt(11)
	v_mov_b64_e32 v[70:71], v[118:119]
	s_waitcnt vmcnt(10)
	v_mov_b64_e32 v[72:73], v[114:115]
	v_cndmask_b32_e32 v197, 0, v89, vcc
	v_cmp_le_i32_e32 vcc, v199, v106
	v_mov_b64_e32 v[60:61], v[128:129]
	v_mov_b64_e32 v[64:65], v[124:125]
	v_cndmask_b32_e32 v198, 0, v82, vcc
	v_cmp_le_i32_e32 vcc, v200, v106
	v_mov_b64_e32 v[68:69], v[120:121]
	v_mov_b64_e32 v[74:75], v[116:117]
	v_cndmask_b32_e32 v199, 0, v83, vcc
	v_cmp_le_i32_e32 vcc, v201, v106
	s_mov_b32 s16, 0x3d372713
	s_mov_b32 s18, 0x3f4c422a
	v_cndmask_b32_e32 v200, 0, v84, vcc
	v_cmp_le_i32_e32 vcc, v202, v106
	v_readlane_b32 s19, v251, 39
	v_readlane_b32 s20, v251, 40
	v_cndmask_b32_e32 v201, 0, v85, vcc
	v_cmp_le_i32_e32 vcc, v203, v106
	v_readlane_b32 s21, v251, 41
	v_readlane_b32 s22, v251, 42
	v_cndmask_b32_e32 v94, 0, v94, vcc
	v_cmp_le_i32_e32 vcc, v208, v106
	v_readlane_b32 s23, v251, 43
	v_readlane_b32 s24, v251, 44
	v_cndmask_b32_e32 v95, 0, v95, vcc
	v_cmp_le_i32_e32 vcc, v209, v106
	v_readlane_b32 s25, v251, 45
	v_readlane_b32 s26, v251, 46
	v_cndmask_b32_e32 v96, 0, v96, vcc
	v_cmp_le_i32_e32 vcc, v210, v106
	v_readlane_b32 s27, v251, 47
	s_nop 0
	v_cndmask_b32_e32 v97, 0, v97, vcc
	v_cmp_le_i32_e32 vcc, v211, v106
	s_nop 1
	v_cndmask_b32_e32 v202, 0, v90, vcc
	v_cmp_le_i32_e32 vcc, v212, v106
	s_nop 1
	v_cndmask_b32_e32 v203, 0, v91, vcc
	v_cmp_le_i32_e32 vcc, v213, v106
	s_nop 1
	v_cndmask_b32_e32 v92, 0, v92, vcc
	v_cmp_le_i32_e32 vcc, v214, v106
	s_nop 1
	v_cndmask_b32_e32 v93, 0, v93, vcc
	v_cmp_le_i32_e32 vcc, v215, v106
	s_nop 1
	v_cndmask_b32_e32 v102, 0, v102, vcc
	v_cmp_le_i32_e32 vcc, v216, v106
	s_nop 1
	v_cndmask_b32_e32 v103, 0, v103, vcc
	v_cmp_le_i32_e32 vcc, v217, v106
	s_nop 1
	v_cndmask_b32_e32 v104, 0, v104, vcc
	v_cmp_le_i32_e32 vcc, v218, v106
	s_nop 1
	v_cndmask_b32_e32 v105, 0, v105, vcc
	v_cmp_le_i32_e32 vcc, v219, v106
	s_nop 1
	v_cndmask_b32_e32 v98, 0, v98, vcc
	v_cmp_le_i32_e32 vcc, v220, v106
	s_nop 1
	v_cndmask_b32_e32 v99, 0, v99, vcc
	v_cmp_le_i32_e32 vcc, v221, v106
	s_nop 1
	v_cndmask_b32_e32 v100, 0, v100, vcc
	v_cmp_le_i32_e32 vcc, v222, v106
	s_nop 1
	v_cndmask_b32_e32 v101, 0, v101, vcc
	s_branch .LBB0_240
	s_nop 0

.LBB0_273:
	v_add_u32_e32 v1, 0x4400, v207
	ds_read2_b32 v[76:77], v1 offset1:68
	ds_read2_b32 v[248:249], v1 offset0:136 offset1:204
	s_waitcnt lgkmcnt(1)
	v_mfma_f32_32x32x2_f32 v[2:17], v76, v98, v[2:17]
	v_mfma_f32_32x32x2_f32 v[2:17], v77, v99, v[2:17]
	s_waitcnt lgkmcnt(0)
	v_mfma_f32_32x32x2_f32 v[2:17], v248, v100, v[2:17]
	v_mfma_f32_32x32x2_f32 v[2:17], v249, v101, v[2:17]
	s_branch .LBB0_239
	s_nop 0
